# attention row-max: dropped two spare wait states after each lane swap
# baseline (speedup 1.0000x reference)
; __device__ __forceinline__ float x4_max(float x) {
;     const unsigned xi = __float_as_uint(x);
;     const auto r = __builtin_amdgcn_permlane32_swap(xi, xi, false, false);
;     const float m = fmaxf(__uint_as_float(r[0]), __uint_as_float(r[1]));
;     const unsigned mi = __float_as_uint(m);
;     const auto r2 = __builtin_amdgcn_permlane16_swap(mi, mi, false, false);
;     return fmaxf(__uint_as_float(r2[0]), __uint_as_float(r2[1]));
; }
; __device__ __forceinline__ void attn_block(const Params& P, int bh, int qb, unsigned char* smem) {
;     ...
;             float mx = -INFINITY;
; #pragma unroll
;             for (int c = 0; c < 4; ++c) {
;                 sa[u][c] -= ck[c];
;                 mx = fmaxf(mx, fmaxf(fmaxf(sa[u][c][0], sa[u][c][1]), fmaxf(sa[u][c][2], sa[u][c][3])));
;             }
;             mx = x4_max(mx);
;             if (__builtin_amdgcn_ballot_w64(mx > m[u]) != 0ull) {
;                 const float mn = fmaxf(m[u], mx);
;                 const float alpha = __builtin_amdgcn_exp2f(m[u] - mn);
;                 m[u] = mn;
; #pragma unroll
;                 for (int c = 0; c < 5; ++c) o[u][c] *= alpha;
;             }
.LBB0_717:
	s_nop 1
	v_max3_f32 v192, v102, v103, v104
	v_max3_f32 v193, v105, v98, v99
	v_max3_f32 v194, v100, v101, v110
	v_max3_f32 v195, v111, v112, v113
	v_max3_f32 v128, v106, v107, v108
	v_max3_f32 v192, v192, v193, v109
	v_max3_f32 v194, v194, v195, v128
	v_max_f32_e32 v192, v192, v194
	v_mov_b32_e32 v193, v192
	s_nop 1
	v_permlane32_swap_b32_e32 v192, v193
	v_max_f32_e32 v192, v192, v193
	v_mov_b32_e32 v193, v192
	s_nop 1
	v_permlane16_swap_b32_e32 v192, v193
	v_max_f32_e32 v192, v192, v193
	v_cmp_gt_f32_e32 vcc, v192, v187
	s_cbranch_vccz .LBB0_719
	v_max_f32_e32 v193, v187, v192
	v_sub_f32_e32 v192, v187, v193
	v_exp_f32_e32 v192, v192
	v_mov_b32_e32 v187, v193
	v_xor_b32_e32 v196, 0x80000000, v193
	v_pk_mul_f32 v[68:69], v[68:69], v[192:193] op_sel_hi:[1,0]
	v_pk_mul_f32 v[66:67], v[66:67], v[192:193] op_sel_hi:[1,0]
	v_pk_mul_f32 v[52:53], v[52:53], v[192:193] op_sel_hi:[1,0]
	v_pk_mul_f32 v[50:51], v[50:51], v[192:193] op_sel_hi:[1,0]
	v_pk_mul_f32 v[48:49], v[48:49], v[192:193] op_sel_hi:[1,0]
	v_pk_mul_f32 v[46:47], v[46:47], v[192:193] op_sel_hi:[1,0]
	v_pk_mul_f32 v[44:45], v[44:45], v[192:193] op_sel_hi:[1,0]
	v_pk_mul_f32 v[42:43], v[42:43], v[192:193] op_sel_hi:[1,0]
	v_pk_mul_f32 v[80:81], v[80:81], v[192:193] op_sel_hi:[1,0]
	v_pk_mul_f32 v[78:79], v[78:79], v[192:193] op_sel_hi:[1,0]
.LBB0_719:
	v_max3_f32 v192, v86, v87, v88
	v_max3_f32 v193, v89, v82, v83
	v_max3_f32 v194, v84, v85, v94
	v_max3_f32 v195, v95, v96, v97
	v_max3_f32 v128, v90, v91, v92
	v_max3_f32 v192, v192, v193, v93
	v_max3_f32 v194, v194, v195, v128
	v_max_f32_e32 v192, v192, v194
	v_mov_b32_e32 v193, v192
	s_nop 1
	v_permlane32_swap_b32_e32 v192, v193
	v_max_f32_e32 v192, v192, v193
	v_mov_b32_e32 v193, v192
	s_nop 1
	v_permlane16_swap_b32_e32 v192, v193
	v_max_f32_e32 v192, v192, v193
	v_cmp_gt_f32_e32 vcc, v192, v2
	s_cbranch_vccz .LBB0_708
	v_max_f32_e32 v193, v2, v192
	v_sub_f32_e32 v192, v2, v193
	v_exp_f32_e32 v192, v192
	v_mov_b32_e32 v2, v193
	v_xor_b32_e32 v230, 0x80000000, v193
	v_pk_mul_f32 v[36:37], v[36:37], v[192:193] op_sel_hi:[1,0]
	v_pk_mul_f32 v[34:35], v[34:35], v[192:193] op_sel_hi:[1,0]
	v_pk_mul_f32 v[32:33], v[32:33], v[192:193] op_sel_hi:[1,0]
	v_pk_mul_f32 v[30:31], v[30:31], v[192:193] op_sel_hi:[1,0]
	v_pk_mul_f32 v[28:29], v[28:29], v[192:193] op_sel_hi:[1,0]
	v_pk_mul_f32 v[26:27], v[26:27], v[192:193] op_sel_hi:[1,0]
	v_pk_mul_f32 v[24:25], v[24:25], v[192:193] op_sel_hi:[1,0]
	v_pk_mul_f32 v[22:23], v[22:23], v[192:193] op_sel_hi:[1,0]
	v_pk_mul_f32 v[40:41], v[40:41], v[192:193] op_sel_hi:[1,0]
	v_pk_mul_f32 v[38:39], v[38:39], v[192:193] op_sel_hi:[1,0]
	s_branch .LBB0_708
